# grid barrier: non-leader workgroups poll the cross-XCD generation word directly, per-XCD release atomic dropped
# baseline (speedup 1.0000x reference)
.LBB0_157:
	s_lshl_b32 s6, s1, 8
	s_add_u32 s6, s96, s6
	s_addc_u32 s7, s97, 0
	v_mov_b32_e32 v2, 0x1000
	v_mov_b32_e32 v4, 1
	global_atomic_add v4, v2, v4, s[6:7] offset:1024 sc0
	v_cvt_f32_u32_e32 v2, v3
	v_sub_u32_e32 v5, 0, v3
	v_rcp_iflag_f32_e32 v2, v2
	s_nop 0
	v_mul_f32_e32 v2, 0x4f7ffffe, v2
	v_cvt_u32_f32_e32 v2, v2
	v_mul_lo_u32 v5, v5, v2
	v_mul_hi_u32 v5, v2, v5
	v_add_u32_e32 v2, v2, v5
	s_waitcnt vmcnt(0)
	v_mul_hi_u32 v2, v4, v2
	v_mul_lo_u32 v5, v2, v3
	v_sub_u32_e32 v5, v4, v5
	v_add_u32_e32 v6, 1, v2
	v_cmp_ge_u32_e32 vcc, v5, v3
	v_add_u32_e32 v4, 1, v4
	s_nop 0
	v_cndmask_b32_e32 v2, v2, v6, vcc
	v_sub_u32_e32 v6, v5, v3
	v_cndmask_b32_e32 v5, v5, v6, vcc
	v_add_u32_e32 v6, 1, v2
	v_cmp_ge_u32_e32 vcc, v5, v3
	s_nop 1
	v_cndmask_b32_e32 v2, v2, v6, vcc
	v_mul_lo_u32 v5, v3, v2
	v_add_u32_e32 v3, v5, v3
	v_cmp_ne_u32_e32 vcc, v4, v3
	s_and_saveexec_b64 s[8:9], vcc
	s_xor_b64 s[8:9], exec, s[8:9]
	s_cbranch_execz .LBB0_171
	s_waitcnt lgkmcnt(0)
	v_mov_b32_e32 v1, 0x7500
	buffer_inv sc1
	global_load_dword v1, v1, s[24:25] sc1
	s_add_u32 s14, s24, 0x7500
	s_addc_u32 s15, s25, 0
	s_waitcnt vmcnt(0)
	v_cmp_eq_u32_e32 vcc, v1, v2
	s_and_saveexec_b64 s[10:11], vcc
	s_cbranch_execz .LBB0_170
	s_add_u32 s12, s24, 0x4200
	s_addc_u32 s13, s25, 0
	s_mov_b32 s21, 1
	s_mov_b64 s[16:17], 0
	v_mov_b32_e32 v1, 0
	s_branch .LBB0_161

.LBB0_188:
	s_or_b64 exec, exec, s[8:9]
	v_mov_b32_e32 v1, 0x2000
	v_mov_b32_e32 v2, 1
	s_waitcnt vmcnt(0)
	s_waitcnt vmcnt(0)

.LBB0_1254:
	s_lshl_b32 s4, s1, 8
	s_add_u32 s4, s96, s4
	s_addc_u32 s5, s97, 0
	v_mov_b32_e32 v2, 0x1000
	v_mov_b32_e32 v4, 1
	global_atomic_add v4, v2, v4, s[4:5] offset:1024 sc0
	v_cvt_f32_u32_e32 v2, v3
	v_sub_u32_e32 v5, 0, v3
	v_rcp_iflag_f32_e32 v2, v2
	s_nop 0
	v_mul_f32_e32 v2, 0x4f7ffffe, v2
	v_cvt_u32_f32_e32 v2, v2
	v_mul_lo_u32 v5, v5, v2
	v_mul_hi_u32 v5, v2, v5
	v_add_u32_e32 v2, v2, v5
	s_waitcnt vmcnt(0)
	v_mul_hi_u32 v2, v4, v2
	v_mul_lo_u32 v5, v2, v3
	v_sub_u32_e32 v5, v4, v5
	v_add_u32_e32 v6, 1, v2
	v_cmp_ge_u32_e32 vcc, v5, v3
	v_add_u32_e32 v4, 1, v4
	s_nop 0
	v_cndmask_b32_e32 v2, v2, v6, vcc
	v_sub_u32_e32 v6, v5, v3
	v_cndmask_b32_e32 v5, v5, v6, vcc
	v_add_u32_e32 v6, 1, v2
	v_cmp_ge_u32_e32 vcc, v5, v3
	s_nop 1
	v_cndmask_b32_e32 v2, v2, v6, vcc
	v_mul_lo_u32 v5, v3, v2
	v_add_u32_e32 v3, v5, v3
	v_cmp_ne_u32_e32 vcc, v4, v3
	s_and_saveexec_b64 s[6:7], vcc
	s_xor_b64 s[6:7], exec, s[6:7]
	s_cbranch_execz .LBB0_1268
	s_waitcnt lgkmcnt(0)
	v_mov_b32_e32 v1, 0x7500
	buffer_inv sc1
	global_load_dword v1, v1, s[24:25] sc1
	s_add_u32 s12, s24, 0x7500
	s_addc_u32 s13, s25, 0
	s_waitcnt vmcnt(0)
	v_cmp_eq_u32_e32 vcc, v1, v2
	s_and_saveexec_b64 s[8:9], vcc
	s_cbranch_execz .LBB0_1267
	s_add_u32 s10, s24, 0x4200
	s_addc_u32 s11, s25, 0
	s_mov_b32 s21, 1
	s_mov_b64 s[14:15], 0
	v_mov_b32_e32 v1, 0
	s_branch .LBB0_1258

.LBB0_1285:
	s_or_b64 exec, exec, s[6:7]
	v_mov_b32_e32 v1, 0x2000
	v_mov_b32_e32 v2, 1
	s_waitcnt vmcnt(0)
	s_waitcnt vmcnt(0)

.LBB0_2145:
	s_lshl_b32 s1, s1, 8
	s_add_u32 s4, s96, s1
	s_addc_u32 s5, s97, 0
	v_mov_b32_e32 v2, 0x1000
	v_mov_b32_e32 v4, 1
	global_atomic_add v4, v2, v4, s[4:5] offset:1024 sc0
	v_cvt_f32_u32_e32 v2, v3
	v_sub_u32_e32 v5, 0, v3
	v_rcp_iflag_f32_e32 v2, v2
	s_nop 0
	v_mul_f32_e32 v2, 0x4f7ffffe, v2
	v_cvt_u32_f32_e32 v2, v2
	v_mul_lo_u32 v5, v5, v2
	v_mul_hi_u32 v5, v2, v5
	v_add_u32_e32 v2, v2, v5
	s_waitcnt vmcnt(0)
	v_mul_hi_u32 v2, v4, v2
	v_mul_lo_u32 v5, v2, v3
	v_sub_u32_e32 v5, v4, v5
	v_add_u32_e32 v6, 1, v2
	v_cmp_ge_u32_e32 vcc, v5, v3
	v_add_u32_e32 v4, 1, v4
	s_nop 0
	v_cndmask_b32_e32 v2, v2, v6, vcc
	v_sub_u32_e32 v6, v5, v3
	v_cndmask_b32_e32 v5, v5, v6, vcc
	v_add_u32_e32 v6, 1, v2
	v_cmp_ge_u32_e32 vcc, v5, v3
	s_nop 1
	v_cndmask_b32_e32 v2, v2, v6, vcc
	v_mul_lo_u32 v5, v3, v2
	v_add_u32_e32 v3, v5, v3
	v_cmp_ne_u32_e32 vcc, v4, v3
	s_and_saveexec_b64 s[6:7], vcc
	s_xor_b64 s[6:7], exec, s[6:7]
	s_cbranch_execz .LBB0_2159
	s_waitcnt lgkmcnt(0)
	v_mov_b32_e32 v1, 0x7500
	buffer_inv sc1
	global_load_dword v1, v1, s[24:25] sc1
	s_add_u32 s12, s24, 0x7500
	s_addc_u32 s13, s25, 0
	s_waitcnt vmcnt(0)
	v_cmp_eq_u32_e32 vcc, v1, v2
	s_and_saveexec_b64 s[8:9], vcc
	s_cbranch_execz .LBB0_2158
	s_add_u32 s10, s24, 0x4200
	s_addc_u32 s11, s25, 0
	s_mov_b32 s1, 1
	s_mov_b64 s[14:15], 0
	v_mov_b32_e32 v1, 0
	s_branch .LBB0_2149
